# code placement: the eight hottest loop heads (GEMM K-loops, flash loops, hyena e-loop) aligned to 64 bytes with s_nop padding
# baseline (speedup 1.0000x reference)
.LBB0_109:
	s_add_u32 s0, s22, 0x100
	s_addc_u32 s1, s23, 0
	s_add_u32 s22, s18, 0xb0080
	s_addc_u32 s23, s19, 0
	v_lshl_add_u64 v[138:139], s[22:23], 0, v[134:135]
	v_lshl_add_u64 v[140:141], s[22:23], 0, v[136:137]
	s_mov_b32 s42, -2
	s_mov_b64 s[22:23], 0
	.p2alignl 6, 3212836864

.LBB0_366:
	v_mov_b64_e32 v[0:1], 0x580
	s_ashr_i32 s11, s10, 31
	v_cmp_lt_i64_e32 vcc, s[14:15], v[0:1]
	s_lshl_b64 s[14:15], s[10:11], 19
	s_add_u32 s14, s42, s14
	s_addc_u32 s15, s43, s15
	s_and_b64 s[16:17], vcc, exec
	s_cselect_b32 s11, s15, s21
	s_cselect_b32 s31, s14, s20
	s_ashr_i32 s9, s8, 31
	s_lshl_b64 s[16:17], s[8:9], 19
	v_readlane_b32 s22, v254, 8
	v_readlane_b32 s23, v254, 9
	s_add_u32 s16, s22, s16
	s_addc_u32 s17, s23, s17
	s_and_b64 s[22:23], vcc, exec
	s_cselect_b32 s9, s17, s19
	s_cselect_b32 s34, s16, s18
	s_add_u32 s35, s18, 0x100
	s_addc_u32 s36, s19, 0
	s_add_u32 s18, s20, 0x40080
	v_mov_b32_e32 v0, 0
	s_addc_u32 s19, s21, 0
	s_mov_b32 s37, -2
	v_mov_b32_e32 v1, v0
	v_mov_b32_e32 v2, v0
	v_mov_b32_e32 v3, v0
	v_mov_b32_e32 v4, v0
	v_mov_b32_e32 v5, v0
	v_mov_b32_e32 v6, v0
	v_mov_b32_e32 v7, v0
	v_mov_b32_e32 v8, v0
	v_mov_b32_e32 v9, v0
	v_mov_b32_e32 v10, v0
	v_mov_b32_e32 v11, v0
	v_mov_b32_e32 v12, v0
	v_mov_b32_e32 v13, v0
	v_mov_b32_e32 v14, v0
	v_mov_b32_e32 v15, v0
	v_mov_b32_e32 v24, v0
	v_mov_b32_e32 v25, v0
	v_mov_b32_e32 v26, v0
	v_mov_b32_e32 v27, v0
	v_mov_b32_e32 v28, v0
	v_mov_b32_e32 v29, v0
	v_mov_b32_e32 v30, v0
	v_mov_b32_e32 v31, v0
	v_mov_b32_e32 v40, v0
	v_mov_b32_e32 v41, v0
	v_mov_b32_e32 v42, v0
	v_mov_b32_e32 v43, v0
	v_mov_b32_e32 v44, v0
	v_mov_b32_e32 v45, v0
	v_mov_b32_e32 v46, v0
	v_mov_b32_e32 v47, v0
	v_mov_b32_e32 v16, v0
	v_mov_b32_e32 v17, v0
	v_mov_b32_e32 v18, v0
	v_mov_b32_e32 v19, v0
	v_mov_b32_e32 v20, v0
	v_mov_b32_e32 v21, v0
	v_mov_b32_e32 v22, v0
	v_mov_b32_e32 v23, v0
	v_mov_b32_e32 v32, v0
	v_mov_b32_e32 v33, v0
	v_mov_b32_e32 v34, v0
	v_mov_b32_e32 v35, v0
	v_mov_b32_e32 v36, v0
	v_mov_b32_e32 v37, v0
	v_mov_b32_e32 v38, v0
	v_mov_b32_e32 v39, v0
	v_mov_b32_e32 v48, v0
	v_mov_b32_e32 v49, v0
	v_mov_b32_e32 v50, v0
	v_mov_b32_e32 v51, v0
	v_mov_b32_e32 v52, v0
	v_mov_b32_e32 v53, v0
	v_mov_b32_e32 v54, v0
	v_mov_b32_e32 v55, v0
	v_mov_b32_e32 v56, v0
	v_mov_b32_e32 v57, v0
	v_mov_b32_e32 v58, v0
	v_mov_b32_e32 v59, v0
	v_mov_b32_e32 v60, v0
	v_mov_b32_e32 v61, v0
	v_mov_b32_e32 v62, v0
	v_mov_b32_e32 v63, v0
	v_mov_b32_e32 v64, v0
	v_mov_b32_e32 v65, v0
	v_mov_b32_e32 v66, v0
	v_mov_b32_e32 v67, v0
	v_mov_b32_e32 v68, v0
	v_mov_b32_e32 v69, v0
	v_mov_b32_e32 v70, v0
	v_mov_b32_e32 v71, v0
	v_mov_b32_e32 v72, v0
	v_mov_b32_e32 v73, v0
	v_mov_b32_e32 v74, v0
	v_mov_b32_e32 v75, v0
	v_mov_b32_e32 v76, v0
	v_mov_b32_e32 v77, v0
	v_mov_b32_e32 v78, v0
	v_mov_b32_e32 v79, v0
	v_mov_b32_e32 v88, v0
	v_mov_b32_e32 v89, v0
	v_mov_b32_e32 v90, v0
	v_mov_b32_e32 v91, v0
	v_mov_b32_e32 v92, v0
	v_mov_b32_e32 v93, v0
	v_mov_b32_e32 v94, v0
	v_mov_b32_e32 v95, v0
	v_mov_b32_e32 v104, v0
	v_mov_b32_e32 v105, v0
	v_mov_b32_e32 v106, v0
	v_mov_b32_e32 v107, v0
	v_mov_b32_e32 v108, v0
	v_mov_b32_e32 v109, v0
	v_mov_b32_e32 v110, v0
	v_mov_b32_e32 v111, v0
	v_mov_b32_e32 v80, v0
	v_mov_b32_e32 v81, v0
	v_mov_b32_e32 v82, v0
	v_mov_b32_e32 v83, v0
	v_mov_b32_e32 v84, v0
	v_mov_b32_e32 v85, v0
	v_mov_b32_e32 v86, v0
	v_mov_b32_e32 v87, v0
	v_mov_b32_e32 v96, v0
	v_mov_b32_e32 v97, v0
	v_mov_b32_e32 v98, v0
	v_mov_b32_e32 v99, v0
	v_mov_b32_e32 v100, v0
	v_mov_b32_e32 v101, v0
	v_mov_b32_e32 v102, v0
	v_mov_b32_e32 v103, v0
	v_mov_b32_e32 v114, v0
	v_mov_b32_e32 v115, v0
	v_mov_b32_e32 v116, v0
	v_mov_b32_e32 v117, v0
	v_mov_b32_e32 v118, v0
	v_mov_b32_e32 v119, v0
	v_mov_b32_e32 v120, v0
	v_mov_b32_e32 v121, v0
	v_mov_b32_e32 v122, v0
	v_mov_b32_e32 v123, v0
	v_mov_b32_e32 v124, v0
	v_mov_b32_e32 v125, v0
	v_mov_b32_e32 v126, v0
	v_mov_b32_e32 v127, v0
	v_mov_b32_e32 v128, v0
	v_mov_b32_e32 v129, v0
	.p2alignl 6, 3212836864

.LBB0_387:
	s_ashr_i32 s23, s22, 31
	s_lshl_b64 s[0:1], s[22:23], s40
	s_add_u32 s24, s15, s0
	s_addc_u32 s25, s11, s1
	s_and_b64 s[0:1], s[8:9], exec
	s_cselect_b32 s0, s25, s19
	s_cselect_b32 s1, s24, s18
	s_ashr_i32 s21, s20, 31
	s_lshl_b64 s[26:27], s[20:21], s40
	s_add_u32 s26, s36, s26
	s_addc_u32 s27, s37, s27
	s_and_b64 s[28:29], s[8:9], exec
	s_cselect_b32 s21, s27, s17
	s_cselect_b32 s23, s26, s16
	s_mov_b32 s30, 0
	s_mov_b64 s[28:29], 0x100
	v_mov_b64_e32 v[138:139], v[136:137]
	v_mov_b64_e32 v[140:141], v[134:135]
	s_mov_b64 s[56:57], 0x100
	.p2alignl 6, 3212836864

.Lhy_prio_skip:
	.p2alignl 6, 3212836864

.LBB0_745:
	v_mov_b32_e32 v177, v192
	v_lshl_add_u64 v[18:19], v[172:173], 1, v[18:19]
	v_ashrrev_i32_e32 v22, 31, v177
	v_lshrrev_b32_e32 v22, 28, v22
	v_add_u32_e32 v22, v177, v22
	v_ashrrev_i32_e32 v50, 4, v22
	v_and_b32_e32 v22, -16, v22
	v_sub_u32_e32 v58, v177, v22
	v_lshlrev_b32_e32 v24, 3, v58
	v_ashrrev_i32_e32 v25, 31, v24
	v_add_u32_e32 v34, 0x200, v177
	v_and_b32_e32 v113, 31, v177
	v_bfe_u32 v51, v177, 5, 1
	v_lshlrev_b64 v[52:53], 1, v[24:25]
	v_ashrrev_i32_e32 v24, 31, v34
	v_mad_u64_u32 v[18:19], s[24:25], v113, s28, v[18:19]
	v_lshlrev_b32_e32 v174, 4, v51
	v_mov_b32_e32 v175, v112
	v_lshrrev_b32_e32 v24, 28, v24
	v_lshl_add_u64 v[46:47], v[18:19], 0, v[174:175]
	v_add_u32_e32 v24, v34, v24
	global_load_dwordx4 v[18:21], v[46:47], off offset:96
	v_ashrrev_i32_e32 v54, 4, v24
	v_and_b32_e32 v24, -16, v24
	v_sub_u32_e32 v59, v34, v24
	v_lshlrev_b32_e32 v26, 3, v59
	v_ashrrev_i32_e32 v62, 3, v177
	v_lshlrev_b32_e32 v32, 3, v177
	v_ashrrev_i32_e32 v63, 3, v34
	v_mad_i64_i32 v[22:23], s[24:25], s22, v50, 0
	v_mad_i64_i32 v[24:25], s[24:25], s22, v54, 0
	v_ashrrev_i32_e32 v27, 31, v26
	v_mad_i64_i32 v[30:31], s[24:25], s20, v62, 0
	v_and_b32_e32 v55, 56, v32
	v_mad_i64_i32 v[34:35], s[24:25], s20, v63, 0
	v_lshl_add_u64 v[22:23], v[22:23], 1, v[180:181]
	v_lshl_add_u64 v[24:25], v[24:25], 1, v[180:181]
	v_lshlrev_b64 v[56:57], 1, v[26:27]
	v_lshl_add_u64 v[30:31], v[30:31], 1, v[16:17]
	v_lshlrev_b32_e32 v32, 1, v55
	v_mov_b32_e32 v33, v112
	v_lshl_add_u64 v[34:35], v[34:35], 1, v[16:17]
	v_lshl_add_u64 v[22:23], v[22:23], 0, v[52:53]
	v_lshl_add_u64 v[26:27], v[24:25], 0, v[56:57]
	v_lshl_add_u64 v[30:31], v[30:31], 0, v[32:33]
	v_lshl_add_u64 v[34:35], v[34:35], 0, v[32:33]
	global_load_dwordx4 v[22:25], v[22:23], off
	s_nop 0
	global_load_dwordx4 v[26:29], v[26:27], off
	s_nop 0
	global_load_dwordx4 v[30:33], v[30:31], off
	s_nop 0
	global_load_dwordx4 v[34:37], v[34:35], off
	s_nop 0
	global_load_dwordx4 v[38:41], v[46:47], off offset:64
	global_load_dwordx4 v[42:45], v[46:47], off offset:32
	s_nop 0
	global_load_dwordx4 v[46:49], v[46:47], off
	v_lshlrev_b32_e32 v201, 4, v58
	v_lshlrev_b32_e32 v213, 4, v59
	s_mov_b32 s24, 0x3e38aa3b
	s_movk_i32 s1, 0x48
	v_lshlrev_b32_e32 v176, 3, v51
	v_mul_lo_u32 v51, v62, s1
	v_add_lshl_u32 v191, v51, v55, 1
	v_mul_lo_u32 v51, v63, s1
	s_movk_i32 s1, 0x110
	v_mul_lo_u32 v195, v50, s1
	v_mul_lo_u32 v202, v54, s1
	s_lshl_b32 s1, s20, 1
	v_add_lshl_u32 v193, v51, v55, 1
	v_ashrrev_i32_e32 v55, 31, v54
	v_lshl_add_u64 v[16:17], v[16:17], 0, s[94:95]
	v_ashrrev_i32_e32 v51, 31, v50
	v_add_u32_e32 v64, 0, v191
	v_add_u32_e32 v65, 0, v193
	v_add3_u32 v66, 0, v201, v195
	v_add3_u32 v67, 0, v213, v202
	v_mov_b32_e32 v190, 0
	v_and_b32_e32 v175, 63, v177
	v_mul_u32_u24_e32 v214, 0x90, v113
	s_add_i32 s0, s0, 1
	s_mov_b32 s5, 0
	v_mov_b32_e32 v68, v190
	v_mov_b32_e32 v69, v190
	v_mov_b32_e32 v70, v190
	v_mov_b32_e32 v71, v190
	v_mov_b32_e32 v72, v190
	v_mov_b32_e32 v73, v190
	v_mov_b32_e32 v74, v190
	v_mov_b32_e32 v75, v190
	v_mov_b32_e32 v76, v190
	v_mov_b32_e32 v77, v190
	v_mov_b32_e32 v78, v190
	v_mov_b32_e32 v79, v190
	s_waitcnt vmcnt(0)
	ds_write_b128 v66, v[22:25]
	ds_write_b128 v67, v[26:29]
	ds_write_b128 v64, v[30:33] offset:17408
	ds_write_b128 v65, v[34:37] offset:17408
	v_lshlrev_b32_e32 v58, 16, v18
	v_and_b32_e32 v59, 0xffff0000, v18
	v_lshlrev_b32_e32 v18, 16, v19
	v_and_b32_e32 v19, 0xffff0000, v19
	v_pk_mul_f32 v[18:19], v[18:19], s[24:25] op_sel_hi:[1,0]
	v_lshlrev_b32_e32 v60, 16, v20
	v_cvt_pk_bf16_f32 v115, v18, v19
	v_lshlrev_b32_e32 v18, 16, v21
	v_and_b32_e32 v19, 0xffff0000, v21
	v_pk_mul_f32 v[18:19], v[18:19], s[24:25] op_sel_hi:[1,0]
	v_and_b32_e32 v61, 0xffff0000, v20
	v_cvt_pk_bf16_f32 v117, v18, v19
	v_lshlrev_b32_e32 v18, 16, v38
	v_and_b32_e32 v19, 0xffff0000, v38
	v_pk_mul_f32 v[18:19], v[18:19], s[24:25] op_sel_hi:[1,0]
	v_pk_mul_f32 v[58:59], v[58:59], s[24:25] op_sel_hi:[1,0]
	v_cvt_pk_bf16_f32 v118, v18, v19
	v_lshlrev_b32_e32 v18, 16, v39
	v_and_b32_e32 v19, 0xffff0000, v39
	v_pk_mul_f32 v[18:19], v[18:19], s[24:25] op_sel_hi:[1,0]
	v_pk_mul_f32 v[60:61], v[60:61], s[24:25] op_sel_hi:[1,0]
	v_cvt_pk_bf16_f32 v119, v18, v19
	v_lshlrev_b32_e32 v18, 16, v40
	v_and_b32_e32 v19, 0xffff0000, v40
	v_pk_mul_f32 v[18:19], v[18:19], s[24:25] op_sel_hi:[1,0]
	v_cvt_pk_bf16_f32 v114, v58, v59
	v_cvt_pk_bf16_f32 v120, v18, v19
	v_lshlrev_b32_e32 v18, 16, v41
	v_and_b32_e32 v19, 0xffff0000, v41
	v_pk_mul_f32 v[18:19], v[18:19], s[24:25] op_sel_hi:[1,0]
	v_cvt_pk_bf16_f32 v116, v60, v61
	v_cvt_pk_bf16_f32 v121, v18, v19
	v_lshlrev_b32_e32 v18, 16, v42
	v_and_b32_e32 v19, 0xffff0000, v42
	v_pk_mul_f32 v[18:19], v[18:19], s[24:25] op_sel_hi:[1,0]
	v_mov_b32_e32 v22, v190
	v_cvt_pk_bf16_f32 v122, v18, v19
	v_lshlrev_b32_e32 v18, 16, v43
	v_and_b32_e32 v19, 0xffff0000, v43
	v_pk_mul_f32 v[18:19], v[18:19], s[24:25] op_sel_hi:[1,0]
	v_mov_b32_e32 v23, v190
	v_cvt_pk_bf16_f32 v123, v18, v19
	v_lshlrev_b32_e32 v18, 16, v44
	v_and_b32_e32 v19, 0xffff0000, v44
	v_pk_mul_f32 v[18:19], v[18:19], s[24:25] op_sel_hi:[1,0]
	v_mov_b32_e32 v24, v190
	v_cvt_pk_bf16_f32 v124, v18, v19
	v_lshlrev_b32_e32 v18, 16, v45
	v_and_b32_e32 v19, 0xffff0000, v45
	v_pk_mul_f32 v[18:19], v[18:19], s[24:25] op_sel_hi:[1,0]
	v_mov_b32_e32 v25, v190
	v_cvt_pk_bf16_f32 v125, v18, v19
	v_lshlrev_b32_e32 v18, 16, v46
	v_and_b32_e32 v19, 0xffff0000, v46
	v_pk_mul_f32 v[18:19], v[18:19], s[24:25] op_sel_hi:[1,0]
	v_mov_b32_e32 v26, v190
	v_cvt_pk_bf16_f32 v126, v18, v19
	v_lshlrev_b32_e32 v18, 16, v47
	v_and_b32_e32 v19, 0xffff0000, v47
	v_pk_mul_f32 v[18:19], v[18:19], s[24:25] op_sel_hi:[1,0]
	v_mov_b32_e32 v27, v190
	v_cvt_pk_bf16_f32 v127, v18, v19
	v_lshlrev_b32_e32 v18, 16, v48
	v_and_b32_e32 v19, 0xffff0000, v48
	v_pk_mul_f32 v[18:19], v[18:19], s[24:25] op_sel_hi:[1,0]
	v_mov_b32_e32 v28, v190
	v_cvt_pk_bf16_f32 v128, v18, v19
	v_lshlrev_b32_e32 v18, 16, v49
	v_and_b32_e32 v19, 0xffff0000, v49
	v_pk_mul_f32 v[18:19], v[18:19], s[24:25] op_sel_hi:[1,0]
	v_mov_b32_e32 v29, v190
	v_cvt_pk_bf16_f32 v129, v18, v19
	v_mul_u32_u24_e32 v18, 0x88, v113
	v_add_lshl_u32 v216, v18, v172, 1
	v_and_b32_e32 v18, 7, v177
	v_lshlrev_b32_e32 v18, 4, v18
	v_mov_b32_e32 v19, v112
	v_mad_i64_i32 v[20:21], s[20:21], s1, v63, v[18:19]
	v_mad_i64_i32 v[18:19], s[20:21], s1, v62, v[18:19]
	v_lshl_add_u64 v[182:183], v[16:17], 0, v[20:21]
	v_lshl_add_u64 v[184:185], v[16:17], 0, v[18:19]
	v_lshl_add_u64 v[16:17], v[54:55], 1, v[168:169]
	v_mad_u64_u32 v[186:187], s[20:21], s22, v16, v[56:57]
	v_mad_i32_i24 v187, s22, v17, v187
	v_lshl_add_u64 v[16:17], v[50:51], 1, v[168:169]
	v_mad_u64_u32 v[188:189], s[24:25], s22, v16, v[52:53]
	v_add_u32_e32 v215, 0x2200, v216
	s_lshl_b32 s20, s22, 7
	s_mov_b32 s21, s96
	v_mad_i32_i24 v189, s22, v17, v189
	v_mov_b32_e32 v16, 0
	v_mov_b32_e32 v17, v190
	v_mov_b32_e32 v18, v190
	v_mov_b32_e32 v19, v190
	v_mov_b32_e32 v20, v190
	v_mov_b32_e32 v21, v190
	v_mov_b32_e32 v30, v190
	v_mov_b32_e32 v31, v190
	v_mov_b32_e32 v32, 0
	v_mov_b32_e32 v33, v190
	v_mov_b32_e32 v34, v190
	v_mov_b32_e32 v35, v190
	v_mov_b32_e32 v36, v190
	v_mov_b32_e32 v37, v190
	v_mov_b32_e32 v38, v190
	v_mov_b32_e32 v39, v190
	v_mov_b32_e32 v40, v190
	v_mov_b32_e32 v41, v190
	v_mov_b32_e32 v42, v190
	v_mov_b32_e32 v43, v190
	v_mov_b32_e32 v44, v190
	v_mov_b32_e32 v45, v190
	v_mov_b32_e32 v46, v190
	v_mov_b32_e32 v47, v190
	v_mov_b32_e32 v48, 0
	v_mov_b32_e32 v49, v190
	v_mov_b32_e32 v50, v190
	v_mov_b32_e32 v51, v190
	v_mov_b32_e32 v52, v190
	v_mov_b32_e32 v53, v190
	v_mov_b32_e32 v54, v190
	v_mov_b32_e32 v55, v190
	v_mov_b32_e32 v56, v190
	v_mov_b32_e32 v57, v190
	v_mov_b32_e32 v58, v190
	v_mov_b32_e32 v59, v190
	v_mov_b32_e32 v60, v190
	v_mov_b32_e32 v61, v190
	v_mov_b32_e32 v62, v190
	v_mov_b32_e32 v63, v190
	v_mov_b32_e32 v64, 0
	v_mov_b32_e32 v65, v190
	v_mov_b32_e32 v66, v190
	v_mov_b32_e32 v67, v190
	s_waitcnt lgkmcnt(0)
	s_barrier
	.p2alignl 6, 3212836864

.Lret_last_tile:
	s_waitcnt vmcnt(0) lgkmcnt(0)
	s_barrier
	v_mfma_f32_32x32x16_bf16 v[48:63], v[244:247], v[180:183], v[48:63]
	v_mfma_f32_32x32x16_bf16 v[32:47], v[248:251], v[180:183], v[32:47]
	v_mfma_f32_32x32x16_bf16 v[16:31], v[72:75], v[180:183], v[16:31]
	v_mfma_f32_32x32x16_bf16 v[0:15], v[76:79], v[180:183], v[0:15]
	s_branch .LBB0_817
	.p2alignl 6, 3212836864

.LBB0_877:
	v_add_f32_e32 v64, 0, v64
	v_add_f32_e32 v64, v65, v64
	v_add_f32_e32 v64, v66, v64
	v_add_f32_e32 v64, v67, v64
	v_add_f32_e32 v64, v68, v64
	v_add_f32_e32 v64, v69, v64
	v_add_f32_e32 v64, v70, v64
	v_add_f32_e32 v64, v71, v64
	v_add_f32_e32 v64, v72, v64
	v_add_f32_e32 v64, v73, v64
	v_add_f32_e32 v64, v74, v64
	v_add_f32_e32 v64, v75, v64
	v_add_f32_e32 v64, v76, v64
	v_add_f32_e32 v64, v77, v64
	v_add_f32_e32 v64, v78, v64
	v_add_f32_e32 v64, v79, v64
	v_add_f32_e32 v48, v48, v64
	v_add_f32_e32 v48, v49, v48
	v_add_f32_e32 v48, v50, v48
	v_add_f32_e32 v48, v51, v48
	v_add_f32_e32 v48, v52, v48
	v_add_f32_e32 v48, v53, v48
	v_add_f32_e32 v48, v54, v48
	v_add_f32_e32 v48, v55, v48
	v_add_f32_e32 v48, v56, v48
	v_add_f32_e32 v48, v57, v48
	v_add_f32_e32 v48, v58, v48
	v_add_f32_e32 v48, v59, v48
	v_add_f32_e32 v48, v60, v48
	v_add_f32_e32 v48, v61, v48
	v_add_f32_e32 v48, v62, v48
	s_add_i32 s24, s24, 2
	v_add_f32_e32 v48, v63, v48
	s_mov_b64 s[0:1], 0x100
	s_cmp_ge_u32 s25, s5
	v_add_f32_e32 v134, v134, v48
	v_lshl_add_u64 v[128:129], v[128:129], 0, s[6:7]
	v_lshl_add_u64 v[130:131], v[130:131], 0, s[0:1]
	s_cselect_b64 s[22:23], -1, 0
	s_waitcnt lgkmcnt(0)
	s_barrier
	s_and_b64 vcc, exec, s[22:23]
	s_cbranch_vccnz .LBB0_870
	.p2alignl 6, 3212836864

.LBB0_1063:
	v_mov_b64_e32 v[0:1], s[8:9]
	s_ashr_i32 s15, s14, 31
	v_cmp_lt_i64_e32 vcc, s[16:17], v[0:1]
	s_lshl_b64 s[16:17], s[14:15], 19
	v_readlane_b32 s18, v254, 37
	v_readlane_b32 s19, v254, 38
	s_add_u32 s16, s18, s16
	s_addc_u32 s17, s19, s17
	s_and_b64 s[18:19], vcc, exec
	s_cselect_b32 s15, s17, s23
	s_cselect_b32 s36, s16, s22
	s_ashr_i32 s13, s12, 31
	s_lshl_b64 s[18:19], s[12:13], 19
	s_add_u32 s18, s90, s18
	s_addc_u32 s19, s91, s19
	s_and_b64 s[24:25], vcc, exec
	s_cselect_b32 s13, s19, s21
	s_cselect_b32 s37, s18, s20
	s_add_u32 s38, s20, 0x100
	s_addc_u32 s39, s21, 0
	s_add_u32 s20, s22, 0x40080
	v_mov_b32_e32 v0, 0
	s_addc_u32 s21, s23, 0
	s_mov_b32 s40, -2
	v_mov_b32_e32 v1, v0
	v_mov_b32_e32 v2, v0
	v_mov_b32_e32 v3, v0
	v_mov_b32_e32 v4, v0
	v_mov_b32_e32 v5, v0
	v_mov_b32_e32 v6, v0
	v_mov_b32_e32 v7, v0
	v_mov_b32_e32 v8, v0
	v_mov_b32_e32 v9, v0
	v_mov_b32_e32 v10, v0
	v_mov_b32_e32 v11, v0
	v_mov_b32_e32 v12, v0
	v_mov_b32_e32 v13, v0
	v_mov_b32_e32 v14, v0
	v_mov_b32_e32 v15, v0
	v_mov_b32_e32 v24, v0
	v_mov_b32_e32 v25, v0
	v_mov_b32_e32 v26, v0
	v_mov_b32_e32 v27, v0
	v_mov_b32_e32 v28, v0
	v_mov_b32_e32 v29, v0
	v_mov_b32_e32 v30, v0
	v_mov_b32_e32 v31, v0
	v_mov_b32_e32 v40, v0
	v_mov_b32_e32 v41, v0
	v_mov_b32_e32 v42, v0
	v_mov_b32_e32 v43, v0
	v_mov_b32_e32 v44, v0
	v_mov_b32_e32 v45, v0
	v_mov_b32_e32 v46, v0
	v_mov_b32_e32 v47, v0
	v_mov_b32_e32 v16, v0
	v_mov_b32_e32 v17, v0
	v_mov_b32_e32 v18, v0
	v_mov_b32_e32 v19, v0
	v_mov_b32_e32 v20, v0
	v_mov_b32_e32 v21, v0
	v_mov_b32_e32 v22, v0
	v_mov_b32_e32 v23, v0
	v_mov_b32_e32 v32, v0
	v_mov_b32_e32 v33, v0
	v_mov_b32_e32 v34, v0
	v_mov_b32_e32 v35, v0
	v_mov_b32_e32 v36, v0
	v_mov_b32_e32 v37, v0
	v_mov_b32_e32 v38, v0
	v_mov_b32_e32 v39, v0
	v_mov_b32_e32 v48, v0
	v_mov_b32_e32 v49, v0
	v_mov_b32_e32 v50, v0
	v_mov_b32_e32 v51, v0
	v_mov_b32_e32 v52, v0
	v_mov_b32_e32 v53, v0
	v_mov_b32_e32 v54, v0
	v_mov_b32_e32 v55, v0
	v_mov_b32_e32 v56, v0
	v_mov_b32_e32 v57, v0
	v_mov_b32_e32 v58, v0
	v_mov_b32_e32 v59, v0
	v_mov_b32_e32 v60, v0
	v_mov_b32_e32 v61, v0
	v_mov_b32_e32 v62, v0
	v_mov_b32_e32 v63, v0
	v_mov_b32_e32 v64, v0
	v_mov_b32_e32 v65, v0
	v_mov_b32_e32 v66, v0
	v_mov_b32_e32 v67, v0
	v_mov_b32_e32 v68, v0
	v_mov_b32_e32 v69, v0
	v_mov_b32_e32 v70, v0
	v_mov_b32_e32 v71, v0
	v_mov_b32_e32 v72, v0
	v_mov_b32_e32 v73, v0
	v_mov_b32_e32 v74, v0
	v_mov_b32_e32 v75, v0
	v_mov_b32_e32 v76, v0
	v_mov_b32_e32 v77, v0
	v_mov_b32_e32 v78, v0
	v_mov_b32_e32 v79, v0
	v_mov_b32_e32 v88, v0
	v_mov_b32_e32 v89, v0
	v_mov_b32_e32 v90, v0
	v_mov_b32_e32 v91, v0
	v_mov_b32_e32 v92, v0
	v_mov_b32_e32 v93, v0
	v_mov_b32_e32 v94, v0
	v_mov_b32_e32 v95, v0
	v_mov_b32_e32 v104, v0
	v_mov_b32_e32 v105, v0
	v_mov_b32_e32 v106, v0
	v_mov_b32_e32 v107, v0
	v_mov_b32_e32 v108, v0
	v_mov_b32_e32 v109, v0
	v_mov_b32_e32 v110, v0
	v_mov_b32_e32 v111, v0
	v_mov_b32_e32 v80, v0
	v_mov_b32_e32 v81, v0
	v_mov_b32_e32 v82, v0
	v_mov_b32_e32 v83, v0
	v_mov_b32_e32 v84, v0
	v_mov_b32_e32 v85, v0
	v_mov_b32_e32 v86, v0
	v_mov_b32_e32 v87, v0
	v_mov_b32_e32 v96, v0
	v_mov_b32_e32 v97, v0
	v_mov_b32_e32 v98, v0
	v_mov_b32_e32 v99, v0
	v_mov_b32_e32 v100, v0
	v_mov_b32_e32 v101, v0
	v_mov_b32_e32 v102, v0
	v_mov_b32_e32 v103, v0
	v_mov_b32_e32 v114, v0
	v_mov_b32_e32 v115, v0
	v_mov_b32_e32 v116, v0
	v_mov_b32_e32 v117, v0
	v_mov_b32_e32 v118, v0
	v_mov_b32_e32 v119, v0
	v_mov_b32_e32 v120, v0
	v_mov_b32_e32 v121, v0
	v_mov_b32_e32 v122, v0
	v_mov_b32_e32 v123, v0
	v_mov_b32_e32 v124, v0
	v_mov_b32_e32 v125, v0
	v_mov_b32_e32 v126, v0
	v_mov_b32_e32 v127, v0
	v_mov_b32_e32 v128, v0
	v_mov_b32_e32 v129, v0
	.p2alignl 6, 3212836864
